# order-diversity groups (P1 convert-first, P2/P4 memory-part-first, P3 scan-last) selected by blockIdx bit 4 instead of bit 3, so adjacent CU slots keep the same order
# baseline (speedup 1.0000x reference)
.LBB0_264:
	s_cmp_lt_i32 s86, 2
	s_cselect_b64 s[0:1], -1, 0
	s_cmp_gt_i32 s87, 1
	s_cselect_b64 s[2:3], -1, 0
	s_and_b64 s[0:1], s[0:1], s[2:3]
	s_andn2_b64 vcc, exec, s[0:1]
	s_cbranch_vccnz .LBB0_335
	s_mov_b32 s94, 2
	s_bitcmp1_b32 s33, 4
	s_cbranch_scc0 .Lmy_p1_pre
	s_mov_b32 s94, 0

.LBB0_335:
	s_cmp_lt_i32 s86, 3
	s_cselect_b64 s[0:1], -1, 0
	s_cmp_gt_i32 s87, 2
	s_cselect_b64 s[2:3], -1, 0
	s_and_b64 s[0:1], s[0:1], s[2:3]
	s_andn2_b64 vcc, exec, s[0:1]
	s_cbranch_vccnz .LBB0_515
	s_mov_b32 s94, 2
	s_bitcmp1_b32 s33, 4
	s_cbranch_scc0 .Lmy_p2_pre
	s_mov_b32 s94, 0

.LBB0_515:
	s_cmp_lt_i32 s86, 4
	s_cselect_b64 s[0:1], -1, 0
	s_cmp_gt_i32 s87, 3
	s_cselect_b64 s[2:3], -1, 0
	s_and_b64 s[0:1], s[0:1], s[2:3]
	s_andn2_b64 vcc, exec, s[0:1]
	s_cbranch_vccnz .LBB0_932
	s_mov_b32 s94, 2
	s_bitcmp1_b32 s33, 4
	s_cbranch_scc0 .Lmy_p3_f
	s_mov_b32 s94, 0

.LBB0_932:
	s_cmp_lt_i32 s86, 5
	s_cselect_b64 s[0:1], -1, 0
	s_cmp_gt_i32 s87, 4
	s_cselect_b64 s[2:3], -1, 0
	s_and_b64 s[0:1], s[0:1], s[2:3]
	s_andn2_b64 vcc, exec, s[0:1]
	s_cbranch_vccnz .LBB0_1057
	s_mov_b32 s70, 2
	s_bitcmp1_b32 s33, 4
	s_cbranch_scc0 .Lmy_p4_pre
	s_mov_b32 s70, 0
